# attention row-max butterfly (ctx+latent): ds_bpermute lane^16/lane^32 exchanges replaced by v_permlane16_swap/v_permlane32_swap on register copies
# speedup vs baseline: 1.0044x; 1.0044x over previous
.LBB0_442:
	ds_read_b128 v[82:85], v77
	ds_read_b128 v[86:89], v77 offset:2048
	ds_read_b128 v[94:97], v78
	ds_read_b128 v[102:105], v78 offset:2048
	s_mov_b32 s2, 0x7060302
	s_waitcnt lgkmcnt(3)
	v_mfma_f32_16x16x32_bf16 v[90:93], v[82:85], v[28:31], 0
	s_cmp_lg_u32 s24, 8
	s_waitcnt lgkmcnt(2)
	v_mfma_f32_16x16x32_bf16 v[98:101], v[86:89], v[28:31], 0
	s_waitcnt lgkmcnt(1)
	v_mfma_f32_16x16x32_bf16 v[90:93], v[94:97], v[32:35], v[90:93]
	s_waitcnt lgkmcnt(0)
	v_mfma_f32_16x16x32_bf16 v[98:101], v[102:105], v[32:35], v[98:101]
	v_mfma_f32_16x16x32_bf16 v[82:85], v[82:85], v[36:39], 0
	s_nop 4
	v_max_f32_e32 v59, v91, v91
	v_max_f32_e32 v61, v90, v90
	v_max_f32_e32 v66, v93, v93
	v_max_f32_e32 v67, v92, v92
	v_max_f32_e32 v106, v101, v101
	v_max_f32_e32 v107, v100, v100
	v_max_f32_e32 v59, v61, v59
	v_max_f32_e32 v61, v67, v66
	v_max_f32_e32 v66, v107, v106
	v_max3_f32 v66, v98, v99, v66
	v_max3_f32 v59, v59, v61, v66
	v_mov_b32_e32 v66, v59
	v_mov_b32_e32 v61, v59
	s_nop 1
	v_permlane16_swap_b32_e32 v66, v61
	v_max_f32_e32 v61, v66, v61
	v_mfma_f32_16x16x32_bf16 v[86:89], v[86:89], v[36:39], 0
	v_add_u32_e32 v67, 0x1000, v79
	ds_read2_b64 v[106:109], v67 offset1:4
	s_waitcnt lgkmcnt(1)
	v_max_f32_e32 v61, v61, v61
	v_max_f32_e32 v59, v59, v61
	v_mov_b32_e32 v66, v59
	v_mov_b32_e32 v61, v59
	s_nop 1
	v_permlane32_swap_b32_e32 v66, v61
	v_max_f32_e32 v61, v66, v61
	v_mfma_f32_16x16x32_bf16 v[82:85], v[94:97], v[44:47], v[82:85]
	s_waitcnt lgkmcnt(0)
	v_max3_f32 v59, v81, v59, v61
	v_sub_f32_e32 v61, v81, v59
	v_sub_f32_e32 v81, v91, v59
	v_mul_f32_e32 v81, 0x3fb8aa3b, v81
	v_exp_f32_e32 v110, v81
	v_sub_f32_e32 v81, v93, v59
	v_mul_f32_e32 v81, 0x3fb8aa3b, v81
	v_exp_f32_e32 v114, v81
	v_sub_f32_e32 v81, v98, v59
	v_mul_f32_e32 v81, 0x3fb8aa3b, v81
	v_exp_f32_e32 v116, v81
	v_sub_f32_e32 v81, v99, v59
	v_mul_f32_e32 v81, 0x3fb8aa3b, v81
	v_exp_f32_e32 v118, v81
	v_sub_f32_e32 v81, v101, v59
	v_mul_f32_e32 v81, 0x3fb8aa3b, v81
	v_sub_f32_e32 v66, v90, v59
	v_sub_f32_e32 v90, v92, v59
	v_exp_f32_e32 v120, v81
	v_sub_f32_e32 v81, v100, v59
	v_mul_f32_e32 v66, 0x3fb8aa3b, v66
	v_mul_f32_e32 v90, 0x3fb8aa3b, v90
	v_mul_f32_e32 v81, 0x3fb8aa3b, v81
	v_exp_f32_e32 v66, v66
	v_exp_f32_e32 v112, v90
	v_exp_f32_e32 v122, v81
	v_bfe_u32 v81, v120, 16, 1
	v_bfe_u32 v90, v118, 16, 1
	v_bfe_u32 v91, v114, 16, 1
	v_bfe_u32 v92, v110, 16, 1
	v_bfe_u32 v93, v122, 16, 1
	v_bfe_u32 v98, v116, 16, 1
	v_bfe_u32 v99, v112, 16, 1
	v_bfe_u32 v100, v66, 16, 1
	v_mfma_f32_16x16x32_bf16 v[86:89], v[102:105], v[44:47], v[86:89]
	v_add3_u32 v101, v110, v92, s56
	v_add3_u32 v91, v114, v91, s56
	v_add3_u32 v90, v118, v90, s56
	v_add3_u32 v81, v120, v81, s56
	v_add3_u32 v100, v66, v100, s56
	v_add3_u32 v99, v112, v99, s56
	v_add3_u32 v92, v116, v98, s56
	v_add3_u32 v93, v122, v93, s56
	v_perm_b32 v93, v81, v93, s2
	v_perm_b32 v92, v90, v92, s2
	v_perm_b32 v91, v91, v99, s2
	v_perm_b32 v90, v101, v100, s2
	v_xor_b32_e32 v98, 16, v67
	ds_read2_b64 v[98:101], v98 offset0:128 offset1:132
	v_max_f32_e32 v67, v83, v83
	v_max_f32_e32 v81, v82, v82
	v_max_f32_e32 v67, v81, v67
	v_max_f32_e32 v81, v85, v85
	v_max_f32_e32 v102, v84, v84
	v_max_f32_e32 v81, v102, v81
	v_max_f32_e32 v102, v89, v89
	v_max_f32_e32 v103, v88, v88
	v_max_f32_e32 v102, v103, v102
	v_max3_f32 v102, v86, v87, v102
	v_max3_f32 v67, v67, v81, v102
	v_mov_b32_e32 v103, v67
	v_mov_b32_e32 v81, v67
	s_nop 1
	v_permlane16_swap_b32_e32 v103, v81
	v_max_f32_e32 v81, v103, v81
	v_mul_f32_e32 v61, 0x3fb8aa3b, v61
	v_exp_f32_e32 v124, v61
	v_add_u32_e32 v61, 0x1800, v79
	ds_read2_b64 v[94:97], v61 offset0:4 offset1:0
	v_xor_b32_e32 v102, 16, v61
	ds_read2_b64 v[102:105], v102 offset0:132 offset1:128
	s_waitcnt lgkmcnt(2)
	v_max_f32_e32 v61, v81, v81
	v_max_f32_e32 v61, v67, v61
	v_mov_b32_e32 v81, v61
	v_mov_b32_e32 v67, v61
	s_nop 1
	v_permlane32_swap_b32_e32 v81, v67
	v_max_f32_e32 v67, v81, v67
	v_pk_mul_f32 v[42:43], v[42:43], v[124:125] op_sel_hi:[1,0]
	v_pk_mul_f32 v[40:41], v[40:41], v[124:125] op_sel_hi:[1,0]
	v_pk_mul_f32 v[26:27], v[26:27], v[124:125] op_sel_hi:[1,0]
	v_pk_mul_f32 v[24:25], v[24:25], v[124:125] op_sel_hi:[1,0]
	s_waitcnt lgkmcnt(0)
	v_max3_f32 v61, v80, v61, v67
	v_sub_f32_e32 v81, v83, v61
	v_mul_f32_e32 v81, 0x3fb8aa3b, v81
	v_exp_f32_e32 v111, v81
	v_sub_f32_e32 v81, v84, v61
	v_sub_f32_e32 v67, v80, v61
	v_mul_f32_e32 v81, 0x3fb8aa3b, v81
	v_mul_f32_e32 v80, 0x3fb8aa3b, v67
	v_sub_f32_e32 v67, v82, v61
	v_exp_f32_e32 v113, v81
	v_sub_f32_e32 v81, v85, v61
	v_mul_f32_e32 v67, 0x3fb8aa3b, v67
	v_mul_f32_e32 v81, 0x3fb8aa3b, v81
	v_exp_f32_e32 v67, v67
	v_exp_f32_e32 v115, v81
	v_sub_f32_e32 v81, v86, v61
	v_sub_f32_e32 v82, v87, v61
	v_sub_f32_e32 v83, v88, v61
	v_sub_f32_e32 v84, v89, v61
	v_mul_f32_e32 v81, 0x3fb8aa3b, v81
	v_mul_f32_e32 v82, 0x3fb8aa3b, v82
	v_mul_f32_e32 v83, 0x3fb8aa3b, v83
	v_mul_f32_e32 v84, 0x3fb8aa3b, v84
	v_exp_f32_e32 v121, v84
	v_exp_f32_e32 v123, v83
	v_exp_f32_e32 v119, v82
	v_exp_f32_e32 v117, v81
	v_pk_mul_f32 v[22:23], v[22:23], v[124:125] op_sel_hi:[1,0]
	v_pk_mul_f32 v[20:21], v[20:21], v[124:125] op_sel_hi:[1,0]
	v_pk_mul_f32 v[18:19], v[18:19], v[124:125] op_sel_hi:[1,0]
	v_pk_mul_f32 v[16:17], v[16:17], v[124:125] op_sel_hi:[1,0]
	v_bfe_u32 v88, v67, 16, 1
	v_exp_f32_e32 v125, v80
	v_add3_u32 v88, v67, v88, s56
	v_pk_add_f32 v[66:67], v[66:67], 0 op_sel_hi:[1,0]
	v_bfe_u32 v81, v121, 16, 1
	v_bfe_u32 v82, v123, 16, 1
	v_bfe_u32 v83, v119, 16, 1
	v_bfe_u32 v84, v117, 16, 1
	v_pk_add_f32 v[66:67], v[110:111], v[66:67]
	v_bfe_u32 v85, v115, 16, 1
	v_bfe_u32 v86, v113, 16, 1
	v_bfe_u32 v87, v111, 16, 1
	v_add3_u32 v84, v117, v84, s56
	v_add3_u32 v89, v119, v83, s56
	v_add3_u32 v82, v123, v82, s56
	v_add3_u32 v81, v121, v81, s56
	v_pk_add_f32 v[66:67], v[112:113], v[66:67]
	v_add3_u32 v87, v111, v87, s56
	v_add3_u32 v86, v113, v86, s56
	v_add3_u32 v85, v115, v85, s56
	v_pk_add_f32 v[66:67], v[114:115], v[66:67]
	v_perm_b32 v83, v81, v82, s2
	v_perm_b32 v82, v89, v84, s2
	v_mov_b32_e32 v84, v125
	v_pk_add_f32 v[66:67], v[116:117], v[66:67]
	v_perm_b32 v81, v85, v86, s2
	v_perm_b32 v80, v87, v88, s2
	v_pk_mul_f32 v[14:15], v[14:15], v[84:85] op_sel_hi:[1,0]
	v_pk_mul_f32 v[12:13], v[12:13], v[84:85] op_sel_hi:[1,0]
	v_pk_mul_f32 v[10:11], v[10:11], v[84:85] op_sel_hi:[1,0]
	v_pk_mul_f32 v[8:9], v[8:9], v[84:85] op_sel_hi:[1,0]
	v_pk_mul_f32 v[6:7], v[6:7], v[84:85] op_sel_hi:[1,0]
	v_pk_mul_f32 v[4:5], v[4:5], v[84:85] op_sel_hi:[1,0]
	v_pk_mul_f32 v[2:3], v[2:3], v[84:85] op_sel_hi:[1,0]
	v_pk_mul_f32 v[0:1], v[0:1], v[84:85] op_sel_hi:[1,0]
	v_mfma_f32_16x16x32_bf16 v[40:43], v[106:109], v[90:93], v[40:43]
	v_add_f32_e64 v66, v118, v66
	v_add_f32_e64 v67, v119, v67
	v_pk_add_f32 v[66:67], v[122:123], v[66:67]
	v_mfma_f32_16x16x32_bf16 v[24:27], v[98:101], v[90:93], v[24:27]
	v_add_f32_e64 v66, v120, v66
	v_add_f32_e64 v67, v121, v67
	v_pk_fma_f32 v[50:51], v[50:51], v[124:125], v[66:67]
	v_mfma_f32_16x16x32_bf16 v[20:23], v[94:97], v[90:93], v[20:23]
	v_mfma_f32_16x16x32_bf16 v[16:19], v[102:105], v[90:93], v[16:19]
	v_mfma_f32_16x16x32_bf16 v[12:15], v[106:109], v[80:83], v[12:15]
	v_mfma_f32_16x16x32_bf16 v[8:11], v[98:101], v[80:83], v[8:11]
	v_mfma_f32_16x16x32_bf16 v[4:7], v[94:97], v[80:83], v[4:7]
	v_mfma_f32_16x16x32_bf16 v[0:3], v[102:105], v[80:83], v[0:3]
	v_mov_b32_e32 v81, v59
	v_mov_b32_e32 v80, v61
	s_cbranch_scc0 .LBB0_447

.LBB0_512:
	s_or_b64 exec, exec, s[28:29]
	v_max_f32_e32 v89, v85, v85
	v_max_f32_e32 v90, v84, v84
	v_max_f32_e32 v89, v90, v89
	v_max_f32_e32 v90, v87, v87
	v_max_f32_e32 v91, v86, v86
	v_max_f32_e32 v90, v91, v90
	v_max_f32_e32 v91, v83, v83
	v_max_f32_e32 v92, v82, v82
	v_max_f32_e32 v91, v92, v91
	v_max3_f32 v91, v80, v81, v91
	v_max3_f32 v89, v89, v90, v91
	v_mov_b32_e32 v91, v89
	v_mov_b32_e32 v90, v89
	s_nop 1
	v_permlane16_swap_b32_e32 v91, v90
	v_max_f32_e32 v90, v91, v90
	v_add_f32_e32 v88, 0, v100
	v_add_f32_e32 v88, v101, v88
	v_add_f32_e32 v88, v102, v88
	v_add_f32_e32 v88, v103, v88
	s_waitcnt lgkmcnt(0)
	v_max_f32_e32 v90, v90, v90
	v_max_f32_e32 v89, v89, v90
	v_mov_b32_e32 v91, v89
	v_mov_b32_e32 v90, v89
	s_nop 1
	v_permlane32_swap_b32_e32 v91, v90
	v_max_f32_e32 v90, v91, v90
	v_add_f32_e32 v88, v152, v88
	v_add_f32_e32 v88, v99, v88
	v_add_f32_e32 v88, v98, v88
	v_add_f32_e32 v88, v97, v88
	s_waitcnt lgkmcnt(0)
	v_max3_f32 v89, v151, v89, v90
	v_sub_f32_e32 v84, v84, v89
	v_mul_f32_e32 v84, 0x3fb8aa3b, v84
	v_sub_f32_e32 v85, v85, v89
	v_exp_f32_e32 v84, v84
	v_mul_f32_e32 v85, 0x3fb8aa3b, v85
	v_sub_f32_e32 v86, v86, v89
	v_exp_f32_e32 v85, v85
	v_mul_f32_e32 v86, 0x3fb8aa3b, v86
	v_sub_f32_e32 v87, v87, v89
	v_exp_f32_e32 v86, v86
	v_mul_f32_e32 v87, 0x3fb8aa3b, v87
	v_sub_f32_e32 v80, v80, v89
	v_exp_f32_e32 v87, v87
	v_mul_f32_e32 v80, 0x3fb8aa3b, v80
	v_sub_f32_e32 v81, v81, v89
	v_add_f32_e32 v91, 0, v84
	v_exp_f32_e32 v92, v80
	v_mul_f32_e32 v81, 0x3fb8aa3b, v81
	v_sub_f32_e32 v82, v82, v89
	v_sub_f32_e32 v83, v83, v89
	v_add_f32_e32 v91, v85, v91
	v_exp_f32_e32 v81, v81
	v_mul_f32_e32 v82, 0x3fb8aa3b, v82
	v_mul_f32_e32 v83, 0x3fb8aa3b, v83
	v_sub_f32_e32 v90, v151, v89
	v_add_f32_e32 v91, v86, v91
	v_exp_f32_e32 v82, v82
	v_exp_f32_e32 v83, v83
	v_mul_f32_e32 v90, 0x3fb8aa3b, v90
	v_add_f32_e32 v91, v87, v91
	v_bfe_u32 v97, v86, 16, 1
	v_add_f32_e32 v80, v92, v91
	v_add3_u32 v97, v86, v97, s56
	v_exp_f32_e32 v86, v90
	v_add_f32_e32 v80, v81, v80
	v_fmac_f32_e32 v88, v126, v96
	v_add_f32_e32 v80, v82, v80
	v_bfe_u32 v91, v83, 16, 1
	v_bfe_u32 v93, v82, 16, 1
	v_bfe_u32 v94, v81, 16, 1
	v_bfe_u32 v95, v92, 16, 1
	v_bfe_u32 v96, v87, 16, 1
	v_bfe_u32 v98, v85, 16, 1
	v_bfe_u32 v99, v84, 16, 1
	v_add_f32_e32 v80, v83, v80
	v_add3_u32 v99, v84, v99, s56
	v_add3_u32 v98, v85, v98, s56
	v_add3_u32 v87, v87, v96, s56
	v_add3_u32 v84, v92, v95, s56
	v_add3_u32 v81, v81, v94, s56
	v_add3_u32 v82, v82, v93, s56
	v_add3_u32 v83, v83, v91, s56
	s_mov_b32 s0, 0x7060302
	v_perm_b32 v85, v83, v82, s0
	v_perm_b32 v84, v81, v84, s0
	v_perm_b32 v83, v87, v97, s0
	v_perm_b32 v82, v98, v99, s0
	v_pk_mul_f32 v[14:15], v[14:15], v[86:87] op_sel_hi:[1,0]
	v_pk_mul_f32 v[12:13], v[12:13], v[86:87] op_sel_hi:[1,0]
	v_pk_mul_f32 v[10:11], v[10:11], v[86:87] op_sel_hi:[1,0]
	v_pk_mul_f32 v[8:9], v[8:9], v[86:87] op_sel_hi:[1,0]
	v_pk_mul_f32 v[6:7], v[6:7], v[86:87] op_sel_hi:[1,0]
	v_pk_mul_f32 v[4:5], v[4:5], v[86:87] op_sel_hi:[1,0]
	v_pk_mul_f32 v[2:3], v[2:3], v[86:87] op_sel_hi:[1,0]
	v_pk_mul_f32 v[0:1], v[0:1], v[86:87] op_sel_hi:[1,0]
	v_mfma_f32_16x16x32_bf16 v[12:15], v[76:79], v[82:85], v[12:15]
	v_fmac_f32_e32 v80, v150, v86
	v_cmp_eq_u32_e64 s[0:1], s27, v124
	v_add_u32_e32 v142, 32, v142
	v_mfma_f32_16x16x32_bf16 v[8:11], v[72:75], v[82:85], v[8:11]
	v_add_u32_e32 v149, 32, v149
	s_or_b64 s[40:41], s[0:1], s[40:41]
	v_mov_b32_e32 v126, v88
	v_mfma_f32_16x16x32_bf16 v[4:7], v[68:71], v[82:85], v[4:7]
	v_mov_b32_e32 v150, v80
	v_mov_b32_e32 v152, v115
	v_mov_b32_e32 v151, v89
	v_mfma_f32_16x16x32_bf16 v[0:3], v[64:67], v[82:85], v[0:3]
	s_mov_b32 s26, s27
	s_andn2_b64 exec, exec, s[40:41]
	s_cbranch_execz .LBB0_523

.LBB0_521:
	s_or_b64 exec, exec, s[28:29]
	v_max_f32_e32 v115, v101, v101
	v_max_f32_e32 v156, v100, v100
	v_max_f32_e32 v115, v156, v115
	v_max_f32_e32 v156, v103, v103
	v_max_f32_e32 v157, v102, v102
	v_max_f32_e32 v156, v157, v156
	v_max_f32_e32 v157, v99, v99
	v_max_f32_e32 v158, v98, v98
	v_max_f32_e32 v157, v158, v157
	v_max3_f32 v157, v96, v97, v157
	v_max3_f32 v115, v115, v156, v157
	v_mov_b32_e32 v157, v115
	v_mov_b32_e32 v156, v115
	s_nop 1
	v_permlane16_swap_b32_e32 v157, v156
	v_max_f32_e32 v156, v157, v156
	v_mfma_f32_16x16x32_bf16 v[80:83], v[80:83], v[40:43], 0
	s_mov_b32 s16, 0x7060302
	s_waitcnt lgkmcnt(0)
	v_max_f32_e32 v156, v156, v156
	v_max_f32_e32 v115, v115, v156
	v_mov_b32_e32 v157, v115
	v_mov_b32_e32 v156, v115
	s_nop 1
	v_permlane32_swap_b32_e32 v157, v156
	v_max_f32_e32 v156, v157, v156
	v_mfma_f32_16x16x32_bf16 v[84:87], v[84:87], v[44:47], v[80:83]
	s_waitcnt lgkmcnt(0)
	v_max3_f32 v115, v152, v115, v156
	v_sub_f32_e32 v152, v152, v115
	v_sub_f32_e32 v97, v97, v115
	v_mul_f32_e32 v156, 0x3fb8aa3b, v152
	v_mul_f32_e32 v152, 0x3fb8aa3b, v97
	v_sub_f32_e32 v97, v98, v115
	v_sub_f32_e32 v96, v96, v115
	v_mul_f32_e32 v98, 0x3fb8aa3b, v97
	v_sub_f32_e32 v97, v99, v115
	v_mul_f32_e32 v96, 0x3fb8aa3b, v96
	v_mul_f32_e32 v97, 0x3fb8aa3b, v97
	v_exp_f32_e32 v97, v97
	v_exp_f32_e32 v99, v152
	v_exp_f32_e32 v152, v96
	v_sub_f32_e32 v100, v100, v115
	v_sub_f32_e32 v101, v101, v115
	v_sub_f32_e32 v102, v102, v115
	v_sub_f32_e32 v103, v103, v115
	v_mul_f32_e32 v100, 0x3fb8aa3b, v100
	v_mul_f32_e32 v101, 0x3fb8aa3b, v101
	v_mul_f32_e32 v102, 0x3fb8aa3b, v102
	v_mul_f32_e32 v103, 0x3fb8aa3b, v103
	v_exp_f32_e32 v100, v100
	v_exp_f32_e32 v101, v101
	v_exp_f32_e32 v102, v102
	v_exp_f32_e32 v103, v103
	v_exp_f32_e32 v98, v98
	v_bfe_u32 v96, v97, 16, 1
	v_bfe_u32 v159, v152, 16, 1
	v_add3_u32 v164, v152, v159, s56
	v_add3_u32 v159, v97, v96, s56
	v_exp_f32_e32 v96, v156
	v_mfma_f32_16x16x32_bf16 v[80:83], v[88:91], v[40:43], 0
	v_bfe_u32 v157, v98, 16, 1
	v_bfe_u32 v158, v99, 16, 1
	v_bfe_u32 v160, v103, 16, 1
	v_bfe_u32 v161, v102, 16, 1
	v_bfe_u32 v162, v101, 16, 1
	v_bfe_u32 v163, v100, 16, 1
	v_add3_u32 v163, v100, v163, s56
	v_add3_u32 v162, v101, v162, s56
	v_add3_u32 v161, v102, v161, s56
	v_add3_u32 v160, v103, v160, s56
	v_add3_u32 v158, v99, v158, s56
	v_add3_u32 v157, v98, v157, s56
	v_perm_b32 v159, v159, v157, s16
	v_perm_b32 v158, v158, v164, s16
	v_perm_b32 v157, v160, v161, s16
	v_perm_b32 v156, v162, v163, s16
	v_pk_mul_f32 v[30:31], v[30:31], v[96:97] op_sel_hi:[1,0]
	v_pk_mul_f32 v[28:29], v[28:29], v[96:97] op_sel_hi:[1,0]
	v_pk_mul_f32 v[26:27], v[26:27], v[96:97] op_sel_hi:[1,0]
	v_pk_mul_f32 v[24:25], v[24:25], v[96:97] op_sel_hi:[1,0]
	v_pk_mul_f32 v[22:23], v[22:23], v[96:97] op_sel_hi:[1,0]
	v_pk_mul_f32 v[20:21], v[20:21], v[96:97] op_sel_hi:[1,0]
	v_pk_mul_f32 v[18:19], v[18:19], v[96:97] op_sel_hi:[1,0]
	v_pk_mul_f32 v[16:17], v[16:17], v[96:97] op_sel_hi:[1,0]
	v_mfma_f32_16x16x32_bf16 v[28:31], v[76:79], v[156:159], v[28:31]
	v_mfma_f32_16x16x32_bf16 v[24:27], v[72:75], v[156:159], v[24:27]
	v_mfma_f32_16x16x32_bf16 v[20:23], v[68:71], v[156:159], v[20:23]
	v_mfma_f32_16x16x32_bf16 v[16:19], v[64:67], v[156:159], v[16:19]
	v_mfma_f32_16x16x32_bf16 v[80:83], v[92:95], v[44:47], v[80:83]
	s_and_saveexec_b64 s[28:29], s[0:1]
	s_cbranch_execz .LBB0_512
	v_sub_u32_e32 v88, v123, v154
	v_sub_u32_e32 v89, 0, v88
	v_max_i32_e32 v88, v88, v89
	s_movk_i32 s0, 0x80
	v_cmp_lt_u32_e64 s[0:1], s0, v88
	v_not_b32_e32 v88, v154
	v_add_u32_e32 v89, v123, v88
	v_sub_u32_e32 v90, 0, v89
	v_mov_b32_e32 v91, 0xf149f2ca
	v_max_i32_e32 v89, v89, v90
	s_movk_i32 s16, 0x81
	v_cndmask_b32_e64 v84, v84, v91, s[0:1]
	v_cmp_gt_u32_e64 s[0:1], s16, v89
	v_sub_u32_e32 v89, v140, v154
	v_sub_u32_e32 v90, 0, v89
	v_max_i32_e32 v89, v89, v90
	v_cndmask_b32_e64 v85, v91, v85, s[0:1]
	v_cmp_gt_u32_e64 s[0:1], s16, v89
	v_sub_u32_e32 v89, v141, v154
	v_sub_u32_e32 v90, 0, v89
	v_max_i32_e32 v89, v89, v90
	v_cndmask_b32_e64 v86, v91, v86, s[0:1]
	v_cmp_gt_u32_e64 s[0:1], s16, v89
	v_sub_u32_e32 v89, 0, v155
	v_max_i32_e32 v89, v155, v89
	v_add_u32_e32 v88, v122, v88
	v_cndmask_b32_e64 v87, v91, v87, s[0:1]
	v_cmp_gt_u32_e64 s[0:1], s16, v89
	v_sub_u32_e32 v89, 0, v88
	v_max_i32_e32 v88, v88, v89
	v_cndmask_b32_e64 v80, v91, v80, s[0:1]
	v_cmp_gt_u32_e64 s[0:1], s16, v88
	v_sub_u32_e32 v88, 0, v153
	v_max_i32_e32 v88, v153, v88
	v_cndmask_b32_e64 v81, v91, v81, s[0:1]
	v_cmp_gt_u32_e64 s[0:1], s16, v88
	v_sub_u32_e32 v88, 0, v117
	v_max_i32_e32 v88, v117, v88
	v_cndmask_b32_e64 v82, v91, v82, s[0:1]
	v_cmp_gt_u32_e64 s[0:1], s16, v88
	s_nop 1
	v_cndmask_b32_e64 v83, v91, v83, s[0:1]
	s_branch .LBB0_512
